# attention: max3 tree for the tile max; dn_chunkprep rhs: five pairs of VN row loads in flight (on top of v8)
# speedup vs baseline: 1.0159x; 1.0159x over previous
; #define MFMA32(a, b, c) __builtin_amdgcn_mfma_f32_32x32x16_bf16((a), (b), (c), 0, 0, 0)
; #define ATT_GLOAD(kt) do { ATT_G1(0, kreg0, vreg0, kt) ATT_G1(1, kreg1, vreg1, kt) } while (0)
; DI void phase_attn(PrmC p, int ai, int layer, int n_items, unsigned char* smem) {
;     ...
;             if (kt + 1 < nkt) ATT_GLOAD(kt + 1);
;             {
;                 f32x16 S0, S1;
; #pragma unroll
;                 for (int i = 0; i < 16; ++i) { S0[i] = 0.f; S1[i] = 0.f; }
; #pragma unroll
;                 for (int ks = 0; ks < 4; ++ks) {
;                     const bf16x8 a0 = *(const bf16x8*)(kb + r * KPITCH + map * 128 + (16 * ks + 8 * hh) * 2);
;                     const bf16x8 a1 = *(const bf16x8*)(kb + (32 + r) * KPITCH + map * 128 + (16 * ks + 8 * hh) * 2);
;                     S0 = MFMA32(a0, qf[ks], S0); S1 = MFMA32(a1, qf[ks], S1); }
;                 float tmax = fmaxf(S0[0], S1[0]);
; #pragma unroll
;                 for (int i = 1; i < 16; ++i) tmax = fmaxf(tmax, fmaxf(S0[i], S1[i]));
;                 if (__any(tmax > m + 8.0f)) {
;                     tmax = fmaxf(tmax, __shfl_xor(tmax, 32));
;                     const float mn = fmaxf(m, tmax), alpha = __builtin_amdgcn_exp2f(m - mn);
;                     m = mn; lsum *= alpha;
; #pragma unroll
;                     for (int nt = 0; nt < 4; ++nt)
; #pragma unroll
;                         for (int i = 0; i < 16; ++i) O[nt][i] *= alpha;
;                 }
.LBB0_461:
	s_bitcmp1_b32 s15, 0
	s_cselect_b32 s17, 0x4400, 0
	v_add_u32_e32 v128, s17, v174
	ds_read_b128 v[66:69], v128
	ds_read_b128 v[114:117], v128 offset:32
	v_lshl_add_u64 v[126:127], v[156:157], 0, s[12:13]
	v_lshl_add_u64 v[184:185], v[160:161], 0, s[12:13]
	s_waitcnt lgkmcnt(1)
	v_mfma_f32_32x32x16_bf16 v[82:97], v[66:69], v[110:113], 0
	ds_read_b128 v[66:69], v128 offset:8704
	ds_read_b128 v[118:121], v128 offset:8736
	s_waitcnt lgkmcnt(1)
	v_mfma_f32_32x32x16_bf16 v[66:81], v[66:69], v[110:113], 0
	s_waitcnt lgkmcnt(0)
	v_mfma_f32_32x32x16_bf16 v[66:81], v[118:121], v[106:109], v[66:81]
	ds_read_b128 v[118:121], v128 offset:64
	v_mfma_f32_32x32x16_bf16 v[82:97], v[114:117], v[106:109], v[82:97]
	v_lshl_add_u64 v[114:115], v[154:155], 0, s[12:13]
	global_load_dwordx4 v[114:117], v[114:115], off
	ds_read_b128 v[122:125], v128 offset:8768
	ds_read_b128 v[180:183], v128 offset:96
	s_waitcnt lgkmcnt(2)
	v_mfma_f32_32x32x16_bf16 v[82:97], v[118:121], v[102:105], v[82:97]
	v_add_co_u32_e32 v118, vcc, s83, v126
	s_nop 1
	v_addc_co_u32_e32 v119, vcc, 0, v127, vcc
	ds_read_b128 v[126:129], v128 offset:8800
	global_load_dwordx4 v[118:121], v[118:119], off offset:128
	s_waitcnt lgkmcnt(2)
	v_mfma_f32_32x32x16_bf16 v[66:81], v[122:125], v[102:105], v[66:81]
	global_load_dwordx4 v[122:125], v[184:185], off
	v_lshl_add_u64 v[184:185], v[158:159], 0, s[12:13]
	v_add_co_u32_e32 v184, vcc, s83, v184
	s_nop 1
	v_addc_co_u32_e32 v185, vcc, 0, v185, vcc
	s_waitcnt lgkmcnt(0)
	v_mfma_f32_32x32x16_bf16 v[66:81], v[126:129], v[98:101], v[66:81]
	global_load_dwordx4 v[126:129], v[184:185], off offset:128
	v_mfma_f32_32x32x16_bf16 v[82:97], v[180:183], v[98:101], v[82:97]
	s_nop 9
	v_max3_f32 v180, v66, v67, v68
	v_max3_f32 v181, v69, v70, v71
	v_max3_f32 v182, v72, v73, v74
	v_max3_f32 v183, v75, v76, v77
	v_max3_f32 v184, v78, v79, v80
	v_max3_f32 v180, v180, v81, v82
	v_max3_f32 v181, v181, v83, v84
	v_max3_f32 v182, v182, v85, v86
	v_max3_f32 v183, v183, v87, v88
	v_max3_f32 v184, v184, v89, v90
	v_max3_f32 v180, v180, v91, v92
	v_max3_f32 v181, v181, v93, v94
	v_max3_f32 v182, v182, v95, v96
	v_max3_f32 v183, v183, v184, v97
	v_max3_f32 v180, v180, v181, v182
	v_max_f32_e32 v180, v180, v183
	v_add_f32_e32 v181, 0x41000000, v153
	v_cmp_gt_f32_e32 vcc, v180, v181
	s_cbranch_vccz .LBB0_460
	ds_bpermute_b32 v181, v162, v180
	s_waitcnt lgkmcnt(0)
	v_max3_f32 v181, v153, v180, v181
	v_sub_f32_e32 v153, v153, v181
	v_exp_f32_e32 v180, v153
	v_mov_b32_e32 v153, v181
	v_pk_mul_f32 v[64:65], v[64:65], v[180:181] op_sel_hi:[1,0]
	v_pk_mul_f32 v[62:63], v[62:63], v[180:181] op_sel_hi:[1,0]
	v_pk_mul_f32 v[60:61], v[60:61], v[180:181] op_sel_hi:[1,0]
	v_pk_mul_f32 v[58:59], v[58:59], v[180:181] op_sel_hi:[1,0]
	v_pk_mul_f32 v[56:57], v[56:57], v[180:181] op_sel_hi:[1,0]
	v_pk_mul_f32 v[54:55], v[54:55], v[180:181] op_sel_hi:[1,0]
	v_pk_mul_f32 v[52:53], v[52:53], v[180:181] op_sel_hi:[1,0]
	v_pk_mul_f32 v[50:51], v[50:51], v[180:181] op_sel_hi:[1,0]
	v_pk_mul_f32 v[48:49], v[48:49], v[180:181] op_sel_hi:[1,0]
	v_pk_mul_f32 v[46:47], v[46:47], v[180:181] op_sel_hi:[1,0]
	v_pk_mul_f32 v[44:45], v[44:45], v[180:181] op_sel_hi:[1,0]
	v_pk_mul_f32 v[42:43], v[42:43], v[180:181] op_sel_hi:[1,0]
	v_pk_mul_f32 v[40:41], v[40:41], v[180:181] op_sel_hi:[1,0]
	v_pk_mul_f32 v[38:39], v[38:39], v[180:181] op_sel_hi:[1,0]
	v_pk_mul_f32 v[36:37], v[36:37], v[180:181] op_sel_hi:[1,0]
	v_pk_mul_f32 v[34:35], v[34:35], v[180:181] op_sel_hi:[1,0]
	v_pk_mul_f32 v[32:33], v[32:33], v[180:181] op_sel_hi:[1,0]
	v_pk_mul_f32 v[30:31], v[30:31], v[180:181] op_sel_hi:[1,0]
	v_pk_mul_f32 v[28:29], v[28:29], v[180:181] op_sel_hi:[1,0]
	v_pk_mul_f32 v[26:27], v[26:27], v[180:181] op_sel_hi:[1,0]
	v_pk_mul_f32 v[24:25], v[24:25], v[180:181] op_sel_hi:[1,0]
	v_pk_mul_f32 v[22:23], v[22:23], v[180:181] op_sel_hi:[1,0]
	v_pk_mul_f32 v[20:21], v[20:21], v[180:181] op_sel_hi:[1,0]
	v_pk_mul_f32 v[18:19], v[18:19], v[180:181] op_sel_hi:[1,0]
	v_pk_mul_f32 v[16:17], v[16:17], v[180:181] op_sel_hi:[1,0]
	v_pk_mul_f32 v[14:15], v[14:15], v[180:181] op_sel_hi:[1,0]
	v_pk_mul_f32 v[12:13], v[12:13], v[180:181] op_sel_hi:[1,0]
	v_pk_mul_f32 v[10:11], v[10:11], v[180:181] op_sel_hi:[1,0]
	v_pk_mul_f32 v[8:9], v[8:9], v[180:181] op_sel_hi:[1,0]
	v_pk_mul_f32 v[6:7], v[6:7], v[180:181] op_sel_hi:[1,0]
	v_pk_mul_f32 v[4:5], v[4:5], v[180:181] op_sel_hi:[1,0]
	v_pk_mul_f32 v[2:3], v[2:3], v[180:181] op_sel_hi:[1,0]
	v_mul_f32_e32 v151, v151, v180
	s_branch .LBB0_460

; template <int D> DI void dn_rhs(float (&x)[64], const float* VN, lf_t Kl, lf_t Gn, lf_t Bn, int row0, int h, int t) {
;             asm volatile("" : "+v"(t));
;             const lf_t Gd = Gn + D * 64, Bd = Bn + D * 64;
;             if (t < 128) {
;                 unsigned voff = (unsigned)(((row0 + (D ? 63 : 0)) * 512 + h * 128 + t) * 4);
; #pragma unroll
;                 for (int pi = 0; pi < 64; ++pi) { const int n = D ? 63 - pi : pi; x[pi] = *(const float*)((const char*)VN + voff) * Bd[n]; voff += D ? -2048 : 2048; asm volatile("" : "+v"(voff)); }
.LBB0_645:
	s_andn2_saveexec_b64 s[20:21], s[20:21]
	s_cbranch_execz .LBB0_647
	s_lshl_b32 s4, s25, 9
	s_or_b32 s4, s39, s4
	v_add_lshl_u32 v0, v0, s4, 2
	v_add_u32_e32 v236, 0x1f800, v0
	global_load_dword v227, v236, s[40:41]
	v_add_u32_e32 v236, 0xfffff800, v236
	global_load_dword v226, v236, s[40:41]
	v_add_u32_e32 v236, 0xfffff800, v236
	global_load_dword v229, v236, s[40:41]
	v_add_u32_e32 v236, 0xfffff800, v236
	global_load_dword v228, v236, s[40:41]
	v_add_u32_e32 v236, 0xfffff800, v236
	global_load_dword v231, v236, s[40:41]
	v_add_u32_e32 v236, 0xfffff800, v236
	global_load_dword v230, v236, s[40:41]
	v_add_u32_e32 v236, 0xfffff800, v236
	global_load_dword v233, v236, s[40:41]
	v_add_u32_e32 v236, 0xfffff800, v236
	global_load_dword v232, v236, s[40:41]
	v_add_u32_e32 v236, 0xfffff800, v236
	global_load_dword v235, v236, s[40:41]
	v_add_u32_e32 v236, 0xfffff800, v236
	global_load_dword v234, v236, s[40:41]
	v_add_u32_e32 v236, 0xfffff800, v236
	v_add_u32_e32 v2, 0x1f800, v0
	v_add_u32_e32 v0, 0x1f000, v0
	ds_read_b32 v5, v104 offset:1020
	ds_read_b32 v4, v104 offset:1016
	v_add_u32_e32 v0, 0xfffff800, v0
	ds_read_b32 v7, v104 offset:1012
	s_waitcnt vmcnt(8) lgkmcnt(1)
	v_pk_mul_f32 v[4:5], v[226:227], v[4:5]
	global_load_dword v227, v236, s[40:41]
	v_add_u32_e32 v236, 0xfffff800, v236
	global_load_dword v226, v236, s[40:41]
	v_add_u32_e32 v236, 0xfffff800, v236
	v_add_u32_e32 v0, 0xfffff800, v0
	ds_read_b32 v6, v104 offset:1008
	v_add_u32_e32 v0, 0xfffff800, v0
	ds_read_b32 v9, v104 offset:1004
	s_waitcnt vmcnt(8) lgkmcnt(1)
	v_pk_mul_f32 v[6:7], v[228:229], v[6:7]
	global_load_dword v229, v236, s[40:41]
	v_add_u32_e32 v236, 0xfffff800, v236
	global_load_dword v228, v236, s[40:41]
	v_add_u32_e32 v236, 0xfffff800, v236
	v_add_u32_e32 v0, 0xfffff800, v0
	ds_read_b32 v8, v104 offset:1000
	v_add_u32_e32 v0, 0xfffff800, v0
	ds_read_b32 v11, v104 offset:996
	v_mov_b32_e32 v50, v7
	v_mov_b32_e32 v51, v6
	s_waitcnt vmcnt(8) lgkmcnt(1)
	v_pk_mul_f32 v[8:9], v[230:231], v[8:9]
	global_load_dword v231, v236, s[40:41]
	v_add_u32_e32 v236, 0xfffff800, v236
	global_load_dword v230, v236, s[40:41]
	v_add_u32_e32 v236, 0xfffff800, v236
	v_add_u32_e32 v0, 0xfffff800, v0
	ds_read_b32 v10, v104 offset:992
	v_add_u32_e32 v0, 0xfffff800, v0
	ds_read_b32 v13, v104 offset:988
	v_mov_b32_e32 v56, v9
	v_mov_b32_e32 v57, v8
	s_waitcnt vmcnt(8) lgkmcnt(1)
	v_pk_mul_f32 v[10:11], v[232:233], v[10:11]
	global_load_dword v233, v236, s[40:41]
	v_add_u32_e32 v236, 0xfffff800, v236
	global_load_dword v232, v236, s[40:41]
	v_add_u32_e32 v236, 0xfffff800, v236
	v_add_u32_e32 v0, 0xfffff800, v0
	ds_read_b32 v12, v104 offset:984
	v_add_u32_e32 v0, 0xfffff800, v0
	ds_read_b32 v15, v104 offset:980
	v_mov_b32_e32 v66, v11
	v_mov_b32_e32 v67, v10
	s_waitcnt vmcnt(8) lgkmcnt(1)
	v_pk_mul_f32 v[12:13], v[234:235], v[12:13]
	global_load_dword v235, v236, s[40:41]
	v_add_u32_e32 v236, 0xfffff800, v236
	global_load_dword v234, v236, s[40:41]
	v_add_u32_e32 v236, 0xfffff800, v236
	v_add_u32_e32 v0, 0xfffff800, v0
	ds_read_b32 v14, v104 offset:976
	v_add_u32_e32 v0, 0xfffff800, v0
	ds_read_b32 v17, v104 offset:972
	v_mov_b32_e32 v64, v13
	v_mov_b32_e32 v65, v12
	s_waitcnt vmcnt(8) lgkmcnt(1)
	v_pk_mul_f32 v[14:15], v[226:227], v[14:15]
	global_load_dword v227, v236, s[40:41]
	v_add_u32_e32 v236, 0xfffff800, v236
	global_load_dword v226, v236, s[40:41]
	v_add_u32_e32 v236, 0xfffff800, v236
	v_add_u32_e32 v0, 0xfffff800, v0
	ds_read_b32 v16, v104 offset:968
	v_add_u32_e32 v0, 0xfffff800, v0
	ds_read_b32 v23, v104 offset:964
	v_mov_b32_e32 v62, v15
	v_mov_b32_e32 v63, v14
	s_waitcnt vmcnt(8) lgkmcnt(1)
	v_pk_mul_f32 v[16:17], v[228:229], v[16:17]
	global_load_dword v229, v236, s[40:41]
	v_add_u32_e32 v236, 0xfffff800, v236
	global_load_dword v228, v236, s[40:41]
	v_add_u32_e32 v236, 0xfffff800, v236
	v_add_u32_e32 v0, 0xfffff800, v0
	ds_read_b32 v22, v104 offset:960
	v_add_u32_e32 v0, 0xfffff800, v0
	ds_read_b32 v25, v104 offset:956
	v_mov_b32_e32 v60, v17
	v_mov_b32_e32 v61, v16
	s_waitcnt vmcnt(8) lgkmcnt(1)
	v_pk_mul_f32 v[22:23], v[230:231], v[22:23]
	global_load_dword v231, v236, s[40:41]
	v_add_u32_e32 v236, 0xfffff800, v236
	global_load_dword v230, v236, s[40:41]
	v_add_u32_e32 v236, 0xfffff800, v236
	v_add_u32_e32 v0, 0xfffff800, v0
	ds_read_b32 v24, v104 offset:952
	v_add_u32_e32 v0, 0xfffff800, v0
	ds_read_b32 v27, v104 offset:948
	v_mov_b32_e32 v58, v23
	v_mov_b32_e32 v59, v22
	s_waitcnt vmcnt(8) lgkmcnt(1)
	v_pk_mul_f32 v[24:25], v[232:233], v[24:25]
	global_load_dword v233, v236, s[40:41]
	v_add_u32_e32 v236, 0xfffff800, v236
	global_load_dword v232, v236, s[40:41]
	v_add_u32_e32 v236, 0xfffff800, v236
	v_add_u32_e32 v0, 0xfffff800, v0
	ds_read_b32 v26, v104 offset:944
	v_add_u32_e32 v0, 0xfffff800, v0
	ds_read_b32 v29, v104 offset:940
	v_mov_b32_e32 v54, v25
	v_mov_b32_e32 v55, v24
	s_waitcnt vmcnt(8) lgkmcnt(1)
	v_pk_mul_f32 v[26:27], v[234:235], v[26:27]
	global_load_dword v235, v236, s[40:41]
	v_add_u32_e32 v236, 0xfffff800, v236
	global_load_dword v234, v236, s[40:41]
	v_add_u32_e32 v236, 0xfffff800, v236
	v_add_u32_e32 v0, 0xfffff800, v0
	ds_read_b32 v28, v104 offset:936
	v_add_u32_e32 v0, 0xfffff800, v0
	ds_read_b32 v31, v104 offset:932
	v_mov_b32_e32 v52, v27
	v_mov_b32_e32 v53, v26
	s_waitcnt vmcnt(8) lgkmcnt(1)
	v_pk_mul_f32 v[28:29], v[226:227], v[28:29]
	global_load_dword v227, v236, s[40:41]
	v_add_u32_e32 v236, 0xfffff800, v236
	global_load_dword v226, v236, s[40:41]
	v_add_u32_e32 v236, 0xfffff800, v236
	v_add_u32_e32 v0, 0xfffff800, v0
	ds_read_b32 v30, v104 offset:928
	v_add_u32_e32 v0, 0xfffff800, v0
	ds_read_b32 v33, v104 offset:924
	v_mov_b32_e32 v48, v29
	v_mov_b32_e32 v49, v28
	s_waitcnt vmcnt(8) lgkmcnt(1)
; template <int D> DI void dn_rhs(float (&x)[64], const float* VN, lf_t Kl, lf_t Gn, lf_t Bn, int row0, int h, int t) {
;             asm volatile("" : "+v"(t));
;             const lf_t Gd = Gn + D * 64, Bd = Bn + D * 64;
;             if (t < 128) {
;                 unsigned voff = (unsigned)(((row0 + (D ? 63 : 0)) * 512 + h * 128 + t) * 4);
; #pragma unroll
;                 for (int pi = 0; pi < 64; ++pi) { const int n = D ? 63 - pi : pi; x[pi] = *(const float*)((const char*)VN + voff) * Bd[n]; voff += D ? -2048 : 2048; asm volatile("" : "+v"(voff)); }
	v_pk_mul_f32 v[30:31], v[228:229], v[30:31]
	global_load_dword v229, v236, s[40:41]
	v_add_u32_e32 v236, 0xfffff800, v236
	global_load_dword v228, v236, s[40:41]
	v_add_u32_e32 v236, 0xfffff800, v236
	v_add_u32_e32 v0, 0xfffff800, v0
	ds_read_b32 v32, v104 offset:920
	v_add_u32_e32 v0, 0xfffff800, v0
	ds_read_b32 v35, v104 offset:916
	v_mov_b32_e32 v46, v31
	v_mov_b32_e32 v47, v30
	s_waitcnt vmcnt(8) lgkmcnt(1)
	v_pk_mul_f32 v[32:33], v[230:231], v[32:33]
	global_load_dword v231, v236, s[40:41]
	v_add_u32_e32 v236, 0xfffff800, v236
	global_load_dword v230, v236, s[40:41]
	v_add_u32_e32 v236, 0xfffff800, v236
	v_add_u32_e32 v0, 0xfffff800, v0
	ds_read_b32 v34, v104 offset:912
	v_add_u32_e32 v0, 0xfffff800, v0
	ds_read_b32 v37, v104 offset:908
	v_mov_b32_e32 v44, v33
	v_mov_b32_e32 v45, v32
	s_waitcnt vmcnt(8) lgkmcnt(1)
	v_pk_mul_f32 v[34:35], v[232:233], v[34:35]
	global_load_dword v233, v236, s[40:41]
	v_add_u32_e32 v236, 0xfffff800, v236
	global_load_dword v232, v236, s[40:41]
	v_add_u32_e32 v236, 0xfffff800, v236
	v_add_u32_e32 v0, 0xfffff800, v0
	ds_read_b32 v36, v104 offset:904
	v_add_u32_e32 v0, 0xfffff800, v0
	ds_read_b32 v39, v104 offset:900
	v_mov_b32_e32 v42, v35
	v_mov_b32_e32 v43, v34
	s_waitcnt vmcnt(8) lgkmcnt(1)
	v_pk_mul_f32 v[36:37], v[234:235], v[36:37]
	global_load_dword v235, v236, s[40:41]
	v_add_u32_e32 v236, 0xfffff800, v236
	global_load_dword v234, v236, s[40:41]
	v_add_u32_e32 v236, 0xfffff800, v236
	v_add_u32_e32 v0, 0xfffff800, v0
	ds_read_b32 v38, v104 offset:896
	v_add_u32_e32 v0, 0xfffff800, v0
	v_mov_b32_e32 v40, v37
	v_mov_b32_e32 v41, v36
	s_waitcnt vmcnt(8) lgkmcnt(0)
	v_pk_mul_f32 v[68:69], v[226:227], v[38:39]
	global_load_dword v227, v236, s[40:41]
	v_add_u32_e32 v236, 0xfffff800, v236
	global_load_dword v226, v236, s[40:41]
	v_add_u32_e32 v236, 0xfffff800, v236
	v_add_u32_e32 v0, 0xfffff800, v0
	ds_read_b32 v39, v104 offset:892
	ds_read_b32 v38, v104 offset:888
	v_add_u32_e32 v0, 0xfffff800, v0
	s_waitcnt vmcnt(8) lgkmcnt(0)
	v_pk_mul_f32 v[70:71], v[228:229], v[38:39]
	global_load_dword v229, v236, s[40:41]
	v_add_u32_e32 v236, 0xfffff800, v236
	global_load_dword v228, v236, s[40:41]
	v_add_u32_e32 v236, 0xfffff800, v236
	v_add_u32_e32 v0, 0xfffff800, v0
	ds_read_b32 v39, v104 offset:884
	ds_read_b32 v38, v104 offset:880
	v_add_u32_e32 v0, 0xfffff800, v0
	v_mov_b32_e32 v36, v71
	v_mov_b32_e32 v37, v70
	s_waitcnt vmcnt(8) lgkmcnt(0)
	v_pk_mul_f32 v[72:73], v[230:231], v[38:39]
	global_load_dword v231, v236, s[40:41]
	v_add_u32_e32 v236, 0xfffff800, v236
	global_load_dword v230, v236, s[40:41]
	v_add_u32_e32 v236, 0xfffff800, v236
	v_add_u32_e32 v0, 0xfffff800, v0
	ds_read_b32 v39, v104 offset:876
	ds_read_b32 v38, v104 offset:872
	v_add_u32_e32 v0, 0xfffff800, v0
	v_mov_b32_e32 v34, v73
	v_mov_b32_e32 v35, v72
	s_waitcnt vmcnt(8) lgkmcnt(0)
	v_pk_mul_f32 v[74:75], v[232:233], v[38:39]
	global_load_dword v233, v236, s[40:41]
	v_add_u32_e32 v236, 0xfffff800, v236
	global_load_dword v232, v236, s[40:41]
	v_add_u32_e32 v236, 0xfffff800, v236
	v_add_u32_e32 v0, 0xfffff800, v0
	ds_read_b32 v39, v104 offset:868
	ds_read_b32 v38, v104 offset:864
	v_add_u32_e32 v0, 0xfffff800, v0
	v_mov_b32_e32 v32, v75
	v_mov_b32_e32 v33, v74
	s_waitcnt vmcnt(8) lgkmcnt(0)
	v_pk_mul_f32 v[76:77], v[234:235], v[38:39]
	global_load_dword v235, v236, s[40:41]
	v_add_u32_e32 v236, 0xfffff800, v236
	global_load_dword v234, v236, s[40:41]
	v_add_u32_e32 v236, 0xfffff800, v236
	v_add_u32_e32 v0, 0xfffff800, v0
	ds_read_b32 v39, v104 offset:860
	ds_read_b32 v38, v104 offset:856
	v_add_u32_e32 v0, 0xfffff800, v0
	v_mov_b32_e32 v30, v77
	v_mov_b32_e32 v31, v76
	s_waitcnt vmcnt(8) lgkmcnt(0)
	v_pk_mul_f32 v[78:79], v[226:227], v[38:39]
	global_load_dword v227, v236, s[40:41]
	v_add_u32_e32 v236, 0xfffff800, v236
	global_load_dword v226, v236, s[40:41]
	v_add_u32_e32 v236, 0xfffff800, v236
	v_add_u32_e32 v0, 0xfffff800, v0
	ds_read_b32 v39, v104 offset:852
	ds_read_b32 v38, v104 offset:848
	v_add_u32_e32 v0, 0xfffff800, v0
	v_mov_b32_e32 v28, v79
	v_mov_b32_e32 v29, v78
	s_waitcnt vmcnt(8) lgkmcnt(0)
; template <int D> DI void dn_rhs(float (&x)[64], const float* VN, lf_t Kl, lf_t Gn, lf_t Bn, int row0, int h, int t) {
;             asm volatile("" : "+v"(t));
;             const lf_t Gd = Gn + D * 64, Bd = Bn + D * 64;
;             if (t < 128) {
;                 unsigned voff = (unsigned)(((row0 + (D ? 63 : 0)) * 512 + h * 128 + t) * 4);
; #pragma unroll
;                 for (int pi = 0; pi < 64; ++pi) { const int n = D ? 63 - pi : pi; x[pi] = *(const float*)((const char*)VN + voff) * Bd[n]; voff += D ? -2048 : 2048; asm volatile("" : "+v"(voff)); }
	v_pk_mul_f32 v[80:81], v[228:229], v[38:39]
	global_load_dword v229, v236, s[40:41]
	v_add_u32_e32 v236, 0xfffff800, v236
	global_load_dword v228, v236, s[40:41]
	v_add_u32_e32 v236, 0xfffff800, v236
	v_add_u32_e32 v0, 0xfffff800, v0
	ds_read_b32 v39, v104 offset:844
	ds_read_b32 v38, v104 offset:840
	v_add_u32_e32 v0, 0xfffff800, v0
	v_mov_b32_e32 v26, v81
	v_mov_b32_e32 v27, v80
	s_waitcnt vmcnt(8) lgkmcnt(0)
	v_pk_mul_f32 v[82:83], v[230:231], v[38:39]
	global_load_dword v231, v236, s[40:41]
	v_add_u32_e32 v236, 0xfffff800, v236
	global_load_dword v230, v236, s[40:41]
	v_add_u32_e32 v236, 0xfffff800, v236
	v_add_u32_e32 v0, 0xfffff800, v0
	ds_read_b32 v39, v104 offset:836
	ds_read_b32 v38, v104 offset:832
	v_add_u32_e32 v0, 0xfffff800, v0
	v_mov_b32_e32 v24, v83
	v_mov_b32_e32 v25, v82
	s_waitcnt vmcnt(8) lgkmcnt(0)
	v_pk_mul_f32 v[84:85], v[232:233], v[38:39]
	global_load_dword v233, v236, s[40:41]
	v_add_u32_e32 v236, 0xfffff800, v236
	global_load_dword v232, v236, s[40:41]
	v_add_u32_e32 v236, 0xfffff800, v236
	v_add_u32_e32 v0, 0xfffff800, v0
	ds_read_b32 v39, v104 offset:828
	ds_read_b32 v38, v104 offset:824
	v_add_u32_e32 v0, 0xfffff800, v0
	v_mov_b32_e32 v22, v85
	v_mov_b32_e32 v23, v84
	s_waitcnt vmcnt(8) lgkmcnt(0)
	v_pk_mul_f32 v[86:87], v[234:235], v[38:39]
	global_load_dword v235, v236, s[40:41]
	v_add_u32_e32 v236, 0xfffff800, v236
	global_load_dword v234, v236, s[40:41]
	v_add_u32_e32 v236, 0xfffff800, v236
	v_add_u32_e32 v0, 0xfffff800, v0
	ds_read_b32 v39, v104 offset:820
	ds_read_b32 v38, v104 offset:816
	v_add_u32_e32 v0, 0xfffff800, v0
	v_mov_b32_e32 v16, v87
	v_mov_b32_e32 v17, v86
	s_waitcnt vmcnt(8) lgkmcnt(0)
	v_pk_mul_f32 v[88:89], v[226:227], v[38:39]
	global_load_dword v227, v236, s[40:41]
	v_add_u32_e32 v236, 0xfffff800, v236
	global_load_dword v226, v236, s[40:41]
	v_add_u32_e32 v236, 0xfffff800, v236
	v_add_u32_e32 v0, 0xfffff800, v0
	ds_read_b32 v39, v104 offset:812
	ds_read_b32 v38, v104 offset:808
	v_add_u32_e32 v0, 0xfffff800, v0
	v_mov_b32_e32 v14, v89
	v_mov_b32_e32 v15, v88
	s_waitcnt vmcnt(8) lgkmcnt(0)
	v_pk_mul_f32 v[90:91], v[228:229], v[38:39]
	global_load_dword v229, v236, s[40:41]
	v_add_u32_e32 v236, 0xfffff800, v236
	global_load_dword v228, v236, s[40:41]
	v_add_u32_e32 v236, 0xfffff800, v236
	v_add_u32_e32 v0, 0xfffff800, v0
	ds_read_b32 v39, v104 offset:804
	ds_read_b32 v38, v104 offset:800
	v_add_u32_e32 v0, 0xfffff800, v0
	v_mov_b32_e32 v12, v91
	v_mov_b32_e32 v13, v90
	s_waitcnt vmcnt(8) lgkmcnt(0)
	v_pk_mul_f32 v[92:93], v[230:231], v[38:39]
	v_add_u32_e32 v0, 0xfffff800, v0
	ds_read_b32 v39, v104 offset:796
	ds_read_b32 v38, v104 offset:792
	v_add_u32_e32 v0, 0xfffff800, v0
	v_mov_b32_e32 v10, v93
	v_mov_b32_e32 v11, v92
	s_waitcnt vmcnt(6) lgkmcnt(0)
	v_pk_mul_f32 v[94:95], v[232:233], v[38:39]
	v_add_u32_e32 v0, 0xfffff800, v0
	ds_read_b32 v39, v104 offset:788
	ds_read_b32 v38, v104 offset:784
	v_add_u32_e32 v0, 0xfffff800, v0
	v_mov_b32_e32 v8, v95
	v_mov_b32_e32 v9, v94
	s_waitcnt vmcnt(4) lgkmcnt(0)
	v_pk_mul_f32 v[96:97], v[234:235], v[38:39]
	v_add_u32_e32 v0, 0xfffff800, v0
	ds_read_b32 v39, v104 offset:780
	ds_read_b32 v38, v104 offset:776
	v_add_u32_e32 v0, 0xfffff800, v0
	v_mov_b32_e32 v6, v97
	v_mov_b32_e32 v7, v96
	s_waitcnt vmcnt(2) lgkmcnt(0)
	v_pk_mul_f32 v[98:99], v[226:227], v[38:39]
	v_add_u32_e32 v0, 0xfffff800, v0
	ds_read_b32 v39, v104 offset:772
	ds_read_b32 v38, v104 offset:768
	v_add_u32_e32 v0, 0xfffff800, v0
	s_waitcnt vmcnt(0) lgkmcnt(0)
	v_pk_mul_f32 v[126:127], v[228:229], v[38:39]
	v_mov_b32_e32 v2, v5
	v_mov_b32_e32 v3, v4
	v_mov_b32_e32 v38, v69
	v_mov_b32_e32 v39, v68
	v_mov_b32_e32 v4, v99
	v_mov_b32_e32 v5, v98
	v_mov_b32_e32 v68, v127
	v_mov_b32_e32 v69, v126

; template <int D> DI void dn_rhs(float (&x)[64], const float* VN, lf_t Kl, lf_t Gn, lf_t Bn, int row0, int h, int t) {
;             asm volatile("" : "+v"(t));
;             const lf_t Gd = Gn + D * 64, Bd = Bn + D * 64;
;             if (t < 128) {
;                 unsigned voff = (unsigned)(((row0 + (D ? 63 : 0)) * 512 + h * 128 + t) * 4);
; #pragma unroll
;                 for (int pi = 0; pi < 64; ++pi) { const int n = D ? 63 - pi : pi; x[pi] = *(const float*)((const char*)VN + voff) * Bd[n]; voff += D ? -2048 : 2048; asm volatile("" : "+v"(voff)); }
.LBB0_651:
	s_andn2_saveexec_b64 s[20:21], s[20:21]
	s_cbranch_execz .LBB0_653
	s_lshl_b32 s4, s25, 9
	s_or_b32 s4, s4, s39
	v_add_lshl_u32 v0, s4, v0, 2
	v_mov_b32_e32 v236, v0
	global_load_dword v227, v236, s[40:41]
	v_add_u32_e32 v236, 0x800, v236
	global_load_dword v226, v236, s[40:41]
	v_add_u32_e32 v236, 0x800, v236
	global_load_dword v229, v236, s[40:41]
	v_add_u32_e32 v236, 0x800, v236
	global_load_dword v228, v236, s[40:41]
	v_add_u32_e32 v236, 0x800, v236
	global_load_dword v231, v236, s[40:41]
	v_add_u32_e32 v236, 0x800, v236
	global_load_dword v230, v236, s[40:41]
	v_add_u32_e32 v236, 0x800, v236
	global_load_dword v233, v236, s[40:41]
	v_add_u32_e32 v236, 0x800, v236
	global_load_dword v232, v236, s[40:41]
	v_add_u32_e32 v236, 0x800, v236
	global_load_dword v235, v236, s[40:41]
	v_add_u32_e32 v236, 0x800, v236
	global_load_dword v234, v236, s[40:41]
	v_add_u32_e32 v236, 0x800, v236
	v_add_u32_e32 v0, 0x800, v0
	ds_read_b32 v5, v104 offset:512
	ds_read_b32 v4, v104 offset:516
	v_add_u32_e32 v0, 0x800, v0
	ds_read_b32 v7, v104 offset:520
	s_waitcnt vmcnt(8) lgkmcnt(1)
	v_pk_mul_f32 v[4:5], v[226:227], v[4:5]
	global_load_dword v227, v236, s[40:41]
	v_add_u32_e32 v236, 0x800, v236
	global_load_dword v226, v236, s[40:41]
	v_add_u32_e32 v236, 0x800, v236
	v_add_u32_e32 v0, 0x800, v0
	ds_read_b32 v6, v104 offset:524
	v_add_u32_e32 v0, 0x800, v0
	ds_read_b32 v9, v104 offset:528
	s_waitcnt vmcnt(8) lgkmcnt(1)
	v_pk_mul_f32 v[6:7], v[228:229], v[6:7]
	global_load_dword v229, v236, s[40:41]
	v_add_u32_e32 v236, 0x800, v236
	global_load_dword v228, v236, s[40:41]
	v_add_u32_e32 v236, 0x800, v236
	v_add_u32_e32 v0, 0x800, v0
	ds_read_b32 v8, v104 offset:532
	v_add_u32_e32 v0, 0x800, v0
	ds_read_b32 v11, v104 offset:536
	v_mov_b32_e32 v50, v7
	v_mov_b32_e32 v51, v6
	s_waitcnt vmcnt(8) lgkmcnt(1)
	v_pk_mul_f32 v[8:9], v[230:231], v[8:9]
	global_load_dword v231, v236, s[40:41]
	v_add_u32_e32 v236, 0x800, v236
	global_load_dword v230, v236, s[40:41]
	v_add_u32_e32 v236, 0x800, v236
	v_add_u32_e32 v0, 0x800, v0
	ds_read_b32 v10, v104 offset:540
	v_add_u32_e32 v0, 0x800, v0
	ds_read_b32 v13, v104 offset:544
	v_mov_b32_e32 v56, v9
	v_mov_b32_e32 v57, v8
	s_waitcnt vmcnt(8) lgkmcnt(1)
	v_pk_mul_f32 v[10:11], v[232:233], v[10:11]
	global_load_dword v233, v236, s[40:41]
	v_add_u32_e32 v236, 0x800, v236
	global_load_dword v232, v236, s[40:41]
	v_add_u32_e32 v236, 0x800, v236
	v_add_u32_e32 v0, 0x800, v0
	ds_read_b32 v12, v104 offset:548
	v_add_u32_e32 v0, 0x800, v0
	ds_read_b32 v15, v104 offset:552
	v_mov_b32_e32 v66, v11
	v_mov_b32_e32 v67, v10
	s_waitcnt vmcnt(8) lgkmcnt(1)
	v_pk_mul_f32 v[12:13], v[234:235], v[12:13]
	global_load_dword v235, v236, s[40:41]
	v_add_u32_e32 v236, 0x800, v236
	global_load_dword v234, v236, s[40:41]
	v_add_u32_e32 v236, 0x800, v236
	v_add_u32_e32 v0, 0x800, v0
	ds_read_b32 v14, v104 offset:556
	v_add_u32_e32 v0, 0x800, v0
	ds_read_b32 v17, v104 offset:560
	v_mov_b32_e32 v64, v13
	v_mov_b32_e32 v65, v12
	s_waitcnt vmcnt(8) lgkmcnt(1)
	v_pk_mul_f32 v[14:15], v[226:227], v[14:15]
	global_load_dword v227, v236, s[40:41]
	v_add_u32_e32 v236, 0x800, v236
	global_load_dword v226, v236, s[40:41]
	v_add_u32_e32 v236, 0x800, v236
	v_add_u32_e32 v0, 0x800, v0
	ds_read_b32 v16, v104 offset:564
	v_add_u32_e32 v0, 0x800, v0
	ds_read_b32 v23, v104 offset:568
	v_mov_b32_e32 v62, v15
	v_mov_b32_e32 v63, v14
	s_waitcnt vmcnt(8) lgkmcnt(1)
	v_pk_mul_f32 v[16:17], v[228:229], v[16:17]
	global_load_dword v229, v236, s[40:41]
	v_add_u32_e32 v236, 0x800, v236
	global_load_dword v228, v236, s[40:41]
	v_add_u32_e32 v236, 0x800, v236
	v_add_u32_e32 v0, 0x800, v0
	ds_read_b32 v22, v104 offset:572
	v_add_u32_e32 v0, 0x800, v0
	ds_read_b32 v25, v104 offset:576
	v_mov_b32_e32 v60, v17
	v_mov_b32_e32 v61, v16
	s_waitcnt vmcnt(8) lgkmcnt(1)
	v_pk_mul_f32 v[22:23], v[230:231], v[22:23]
	global_load_dword v231, v236, s[40:41]
	v_add_u32_e32 v236, 0x800, v236
	global_load_dword v230, v236, s[40:41]
	v_add_u32_e32 v236, 0x800, v236
	v_add_u32_e32 v0, 0x800, v0
	ds_read_b32 v24, v104 offset:580
	v_add_u32_e32 v0, 0x800, v0
	ds_read_b32 v27, v104 offset:584
	v_mov_b32_e32 v58, v23
	v_mov_b32_e32 v59, v22
	s_waitcnt vmcnt(8) lgkmcnt(1)
	v_pk_mul_f32 v[24:25], v[232:233], v[24:25]
	global_load_dword v233, v236, s[40:41]
	v_add_u32_e32 v236, 0x800, v236
	global_load_dword v232, v236, s[40:41]
	v_add_u32_e32 v236, 0x800, v236
	v_add_u32_e32 v0, 0x800, v0
	ds_read_b32 v26, v104 offset:588
	v_add_u32_e32 v0, 0x800, v0
	ds_read_b32 v29, v104 offset:592
	v_mov_b32_e32 v54, v25
	v_mov_b32_e32 v55, v24
	s_waitcnt vmcnt(8) lgkmcnt(1)
	v_pk_mul_f32 v[26:27], v[234:235], v[26:27]
	global_load_dword v235, v236, s[40:41]
	v_add_u32_e32 v236, 0x800, v236
	global_load_dword v234, v236, s[40:41]
	v_add_u32_e32 v236, 0x800, v236
	v_add_u32_e32 v0, 0x800, v0
	ds_read_b32 v28, v104 offset:596
	v_add_u32_e32 v0, 0x800, v0
	ds_read_b32 v31, v104 offset:600
	v_mov_b32_e32 v52, v27
	v_mov_b32_e32 v53, v26
	s_waitcnt vmcnt(8) lgkmcnt(1)
	v_pk_mul_f32 v[28:29], v[226:227], v[28:29]
	global_load_dword v227, v236, s[40:41]
	v_add_u32_e32 v236, 0x800, v236
	global_load_dword v226, v236, s[40:41]
	v_add_u32_e32 v236, 0x800, v236
	v_add_u32_e32 v0, 0x800, v0
	ds_read_b32 v30, v104 offset:604
	v_add_u32_e32 v0, 0x800, v0
	ds_read_b32 v33, v104 offset:608
	v_mov_b32_e32 v48, v29
	v_mov_b32_e32 v49, v28
	s_waitcnt vmcnt(8) lgkmcnt(1)
	v_pk_mul_f32 v[30:31], v[228:229], v[30:31]
	global_load_dword v229, v236, s[40:41]
	v_add_u32_e32 v236, 0x800, v236
	global_load_dword v228, v236, s[40:41]
	v_add_u32_e32 v236, 0x800, v236
	v_add_u32_e32 v0, 0x800, v0
	ds_read_b32 v32, v104 offset:612
	v_add_u32_e32 v0, 0x800, v0
	ds_read_b32 v35, v104 offset:616
	v_mov_b32_e32 v46, v31
	v_mov_b32_e32 v47, v30
	s_waitcnt vmcnt(8) lgkmcnt(1)
; template <int D> DI void dn_rhs(float (&x)[64], const float* VN, lf_t Kl, lf_t Gn, lf_t Bn, int row0, int h, int t) {
;             asm volatile("" : "+v"(t));
;             const lf_t Gd = Gn + D * 64, Bd = Bn + D * 64;
;             if (t < 128) {
;                 unsigned voff = (unsigned)(((row0 + (D ? 63 : 0)) * 512 + h * 128 + t) * 4);
; #pragma unroll
;                 for (int pi = 0; pi < 64; ++pi) { const int n = D ? 63 - pi : pi; x[pi] = *(const float*)((const char*)VN + voff) * Bd[n]; voff += D ? -2048 : 2048; asm volatile("" : "+v"(voff)); }
	v_pk_mul_f32 v[32:33], v[230:231], v[32:33]
	global_load_dword v231, v236, s[40:41]
	v_add_u32_e32 v236, 0x800, v236
	global_load_dword v230, v236, s[40:41]
	v_add_u32_e32 v236, 0x800, v236
	v_add_u32_e32 v0, 0x800, v0
	ds_read_b32 v34, v104 offset:620
	v_add_u32_e32 v0, 0x800, v0
	ds_read_b32 v37, v104 offset:624
	v_mov_b32_e32 v44, v33
	v_mov_b32_e32 v45, v32
	s_waitcnt vmcnt(8) lgkmcnt(1)
	v_pk_mul_f32 v[34:35], v[232:233], v[34:35]
	global_load_dword v233, v236, s[40:41]
	v_add_u32_e32 v236, 0x800, v236
	global_load_dword v232, v236, s[40:41]
	v_add_u32_e32 v236, 0x800, v236
	v_add_u32_e32 v0, 0x800, v0
	ds_read_b32 v36, v104 offset:628
	v_add_u32_e32 v0, 0x800, v0
	ds_read_b32 v39, v104 offset:632
	v_mov_b32_e32 v42, v35
	v_mov_b32_e32 v43, v34
	s_waitcnt vmcnt(8) lgkmcnt(1)
	v_pk_mul_f32 v[36:37], v[234:235], v[36:37]
	global_load_dword v235, v236, s[40:41]
	v_add_u32_e32 v236, 0x800, v236
	global_load_dword v234, v236, s[40:41]
	v_add_u32_e32 v236, 0x800, v236
	v_add_u32_e32 v0, 0x800, v0
	ds_read_b32 v38, v104 offset:636
	v_add_u32_e32 v0, 0x800, v0
	v_mov_b32_e32 v40, v37
	v_mov_b32_e32 v41, v36
	s_waitcnt vmcnt(8) lgkmcnt(0)
	v_pk_mul_f32 v[68:69], v[226:227], v[38:39]
	global_load_dword v227, v236, s[40:41]
	v_add_u32_e32 v236, 0x800, v236
	global_load_dword v226, v236, s[40:41]
	v_add_u32_e32 v236, 0x800, v236
	v_add_u32_e32 v0, 0x800, v0
	ds_read_b32 v39, v104 offset:640
	ds_read_b32 v38, v104 offset:644
	v_add_u32_e32 v0, 0x800, v0
	s_waitcnt vmcnt(8) lgkmcnt(0)
	v_pk_mul_f32 v[70:71], v[228:229], v[38:39]
	global_load_dword v229, v236, s[40:41]
	v_add_u32_e32 v236, 0x800, v236
	global_load_dword v228, v236, s[40:41]
	v_add_u32_e32 v236, 0x800, v236
	v_add_u32_e32 v0, 0x800, v0
	ds_read_b32 v39, v104 offset:648
	ds_read_b32 v38, v104 offset:652
	v_add_u32_e32 v0, 0x800, v0
	v_mov_b32_e32 v36, v71
	v_mov_b32_e32 v37, v70
	s_waitcnt vmcnt(8) lgkmcnt(0)
	v_pk_mul_f32 v[72:73], v[230:231], v[38:39]
	global_load_dword v231, v236, s[40:41]
	v_add_u32_e32 v236, 0x800, v236
	global_load_dword v230, v236, s[40:41]
	v_add_u32_e32 v236, 0x800, v236
	v_add_u32_e32 v0, 0x800, v0
	ds_read_b32 v39, v104 offset:656
	ds_read_b32 v38, v104 offset:660
	v_add_u32_e32 v0, 0x800, v0
	v_mov_b32_e32 v34, v73
	v_mov_b32_e32 v35, v72
	s_waitcnt vmcnt(8) lgkmcnt(0)
	v_pk_mul_f32 v[74:75], v[232:233], v[38:39]
	global_load_dword v233, v236, s[40:41]
	v_add_u32_e32 v236, 0x800, v236
	global_load_dword v232, v236, s[40:41]
	v_add_u32_e32 v236, 0x800, v236
	v_add_u32_e32 v0, 0x800, v0
	ds_read_b32 v39, v104 offset:664
	ds_read_b32 v38, v104 offset:668
	v_add_u32_e32 v0, 0x800, v0
	v_mov_b32_e32 v32, v75
	v_mov_b32_e32 v33, v74
	s_waitcnt vmcnt(8) lgkmcnt(0)
	v_pk_mul_f32 v[76:77], v[234:235], v[38:39]
	global_load_dword v235, v236, s[40:41]
	v_add_u32_e32 v236, 0x800, v236
	global_load_dword v234, v236, s[40:41]
	v_add_u32_e32 v236, 0x800, v236
	v_add_u32_e32 v0, 0x800, v0
	ds_read_b32 v39, v104 offset:672
	ds_read_b32 v38, v104 offset:676
	v_add_u32_e32 v0, 0x800, v0
	v_mov_b32_e32 v30, v77
	v_mov_b32_e32 v31, v76
	s_waitcnt vmcnt(8) lgkmcnt(0)
	v_pk_mul_f32 v[78:79], v[226:227], v[38:39]
	global_load_dword v227, v236, s[40:41]
	v_add_u32_e32 v236, 0x800, v236
	global_load_dword v226, v236, s[40:41]
	v_add_u32_e32 v236, 0x800, v236
	v_add_u32_e32 v0, 0x800, v0
	ds_read_b32 v39, v104 offset:680
	ds_read_b32 v38, v104 offset:684
	v_add_u32_e32 v0, 0x800, v0
	v_mov_b32_e32 v28, v79
	v_mov_b32_e32 v29, v78
	s_waitcnt vmcnt(8) lgkmcnt(0)
	v_pk_mul_f32 v[80:81], v[228:229], v[38:39]
	global_load_dword v229, v236, s[40:41]
	v_add_u32_e32 v236, 0x800, v236
	global_load_dword v228, v236, s[40:41]
	v_add_u32_e32 v236, 0x800, v236
	v_add_u32_e32 v0, 0x800, v0
	ds_read_b32 v39, v104 offset:688
	ds_read_b32 v38, v104 offset:692
	v_add_u32_e32 v0, 0x800, v0
	v_mov_b32_e32 v26, v81
	v_mov_b32_e32 v27, v80
	s_waitcnt vmcnt(8) lgkmcnt(0)
	v_pk_mul_f32 v[82:83], v[230:231], v[38:39]
	global_load_dword v231, v236, s[40:41]
	v_add_u32_e32 v236, 0x800, v236
	global_load_dword v230, v236, s[40:41]
	v_add_u32_e32 v236, 0x800, v236
	v_add_u32_e32 v0, 0x800, v0
	ds_read_b32 v39, v104 offset:696
	ds_read_b32 v38, v104 offset:700
	v_add_u32_e32 v0, 0x800, v0
	v_mov_b32_e32 v24, v83
	v_mov_b32_e32 v25, v82
	s_waitcnt vmcnt(8) lgkmcnt(0)
	v_pk_mul_f32 v[84:85], v[232:233], v[38:39]
	global_load_dword v233, v236, s[40:41]
	v_add_u32_e32 v236, 0x800, v236
	global_load_dword v232, v236, s[40:41]
	v_add_u32_e32 v236, 0x800, v236
	v_add_u32_e32 v0, 0x800, v0
	ds_read_b32 v39, v104 offset:704
	ds_read_b32 v38, v104 offset:708
	v_add_u32_e32 v0, 0x800, v0
	v_mov_b32_e32 v22, v85
	v_mov_b32_e32 v23, v84
	s_waitcnt vmcnt(8) lgkmcnt(0)
	v_pk_mul_f32 v[86:87], v[234:235], v[38:39]
	global_load_dword v235, v236, s[40:41]
	v_add_u32_e32 v236, 0x800, v236
	global_load_dword v234, v236, s[40:41]
	v_add_u32_e32 v236, 0x800, v236
	v_add_u32_e32 v0, 0x800, v0
	ds_read_b32 v39, v104 offset:712
	ds_read_b32 v38, v104 offset:716
	v_add_u32_e32 v0, 0x800, v0
	v_mov_b32_e32 v16, v87
	v_mov_b32_e32 v17, v86
	s_waitcnt vmcnt(8) lgkmcnt(0)
	v_pk_mul_f32 v[88:89], v[226:227], v[38:39]
	global_load_dword v227, v236, s[40:41]
	v_add_u32_e32 v236, 0x800, v236
	global_load_dword v226, v236, s[40:41]
	v_add_u32_e32 v236, 0x800, v236
	v_add_u32_e32 v0, 0x800, v0
	ds_read_b32 v39, v104 offset:720
	ds_read_b32 v38, v104 offset:724
	v_add_u32_e32 v0, 0x800, v0
	v_mov_b32_e32 v14, v89
	v_mov_b32_e32 v15, v88
	s_waitcnt vmcnt(8) lgkmcnt(0)
	v_pk_mul_f32 v[90:91], v[228:229], v[38:39]
	global_load_dword v229, v236, s[40:41]
	v_add_u32_e32 v236, 0x800, v236
	global_load_dword v228, v236, s[40:41]
	v_add_u32_e32 v236, 0x800, v236
	v_add_u32_e32 v0, 0x800, v0
	ds_read_b32 v39, v104 offset:728
	ds_read_b32 v38, v104 offset:732
	v_add_u32_e32 v0, 0x800, v0
	v_mov_b32_e32 v12, v91
	v_mov_b32_e32 v13, v90
	s_waitcnt vmcnt(8) lgkmcnt(0)
	v_pk_mul_f32 v[92:93], v[230:231], v[38:39]
	v_add_u32_e32 v0, 0x800, v0
	ds_read_b32 v39, v104 offset:736
	ds_read_b32 v38, v104 offset:740
	v_add_u32_e32 v0, 0x800, v0
	v_mov_b32_e32 v10, v93
	v_mov_b32_e32 v11, v92
	s_waitcnt vmcnt(6) lgkmcnt(0)
	v_pk_mul_f32 v[94:95], v[232:233], v[38:39]
	v_add_u32_e32 v0, 0x800, v0
	ds_read_b32 v39, v104 offset:744
	ds_read_b32 v38, v104 offset:748
	v_add_u32_e32 v0, 0x800, v0
	v_mov_b32_e32 v8, v95
	v_mov_b32_e32 v9, v94
	s_waitcnt vmcnt(4) lgkmcnt(0)
	v_pk_mul_f32 v[96:97], v[234:235], v[38:39]
	v_add_u32_e32 v0, 0x800, v0
	ds_read_b32 v39, v104 offset:752
	ds_read_b32 v38, v104 offset:756
	v_add_u32_e32 v0, 0x800, v0
	v_mov_b32_e32 v6, v97
	v_mov_b32_e32 v7, v96
	s_waitcnt vmcnt(2) lgkmcnt(0)
	v_pk_mul_f32 v[98:99], v[226:227], v[38:39]
	v_add_u32_e32 v0, 0x800, v0
	ds_read_b32 v39, v104 offset:760
	ds_read_b32 v38, v104 offset:764
	v_add_u32_e32 v0, 0x800, v0
	s_waitcnt vmcnt(0) lgkmcnt(0)
	v_pk_mul_f32 v[126:127], v[228:229], v[38:39]
	v_mov_b32_e32 v2, v5
	v_mov_b32_e32 v3, v4
	v_mov_b32_e32 v38, v69
	v_mov_b32_e32 v39, v68
	v_mov_b32_e32 v4, v99
	v_mov_b32_e32 v5, v98
	v_mov_b32_e32 v68, v127
	v_mov_b32_e32 v69, v126
